# selected-branch waves with work at s_setprio 2, window loop at 1
# speedup vs baseline: 1.0017x; 1.0017x over previous
.Lsel_have_words:
	v_and_b32_e32 v0, s70, v250
	v_cmp_ne_u32_e64 s[50:51], 0, v0
	v_and_b32_e32 v0, s70, v251
	v_cmp_ne_u32_e64 s[48:49], 0, v0
	v_and_b32_e32 v0, s70, v249
	v_cmp_ne_u32_e64 s[46:47], 0, v0
	v_and_b32_e32 v0, s70, v248
	v_cmp_ne_u32_e64 s[42:43], 0, v0
	s_mov_b64 s[86:87], s[50:51]
	s_mov_b64 s[88:89], s[48:49]
	s_mov_b64 s[90:91], s[46:47]
	s_mov_b64 s[92:93], s[42:43]
	s_or_b64 s[2:3], s[48:49], s[50:51]
	s_or_b64 s[2:3], s[2:3], s[46:47]
	s_or_b64 s[2:3], s[2:3], s[42:43]
	s_cmp_eq_u64 s[2:3], 0
	s_cbranch_scc1 .LBB0_810
	s_setprio 2
	ds_read_b128 v[182:185], v246
	ds_read_b128 v[178:181], v246 offset:2048
	ds_read_b128 v[186:189], v247
	ds_read_b128 v[174:177], v247 offset:2048
	ds_read_b128 v[158:161], v244 offset:4096
	ds_read_b128 v[162:165], v244 offset:5120
	ds_read_b128 v[166:169], v244 offset:6144
	ds_read_b128 v[170:173], v244 offset:7168
	s_add_i32 s2, s28, 0xfffffeff
	s_cmp_le_i32 s2, s26
	s_cselect_b64 s[2:3], -1, 0
	v_cndmask_b32_e64 v0, 0, 1, s[2:3]
	s_cmp_eq_u64 s[50:51], 0
	v_cmp_ne_u32_e64 s[44:45], 1, v0
	s_cbranch_scc1 .LBB0_767
	v_cndmask_b32_e64 v190, v194, 0, s[50:51]
	v_cndmask_b32_e64 v191, v194, 0, s[50:51]
	v_cndmask_b32_e64 v192, v194, 0, s[50:51]
	v_cndmask_b32_e64 v193, v194, 0, s[50:51]
	s_nop 0
	s_waitcnt lgkmcnt(7)
	v_mfma_f32_16x16x32_bf16 v[0:3], v[182:185], v[104:107], v[190:193]
	s_and_b64 vcc, exec, s[44:45]
	s_mov_b64 s[64:65], -1
	s_waitcnt lgkmcnt(6)
	v_mfma_f32_16x16x32_bf16 v[4:7], v[178:181], v[104:107], v[190:193]
	s_waitcnt lgkmcnt(5)
	v_mfma_f32_16x16x32_bf16 v[0:3], v[186:189], v[108:111], v[0:3]
	s_waitcnt lgkmcnt(4)
	v_mfma_f32_16x16x32_bf16 v[4:7], v[174:177], v[108:111], v[4:7]
	s_nop 5
	v_exp_f32_e32 v0, v0
	v_exp_f32_e32 v1, v1
	v_exp_f32_e32 v2, v2
	v_exp_f32_e32 v3, v3
	v_exp_f32_e32 v4, v4
	v_exp_f32_e32 v5, v5
	v_exp_f32_e32 v6, v6
	v_exp_f32_e32 v7, v7
	s_cbranch_vccz .LBB0_766

.LBB0_815:
	s_setprio 0
	s_add_i32 s2, s27, -3
	s_lshl_b32 s64, 1, s2
	v_and_b32_e32 v0, s64, v250
	v_cmp_ne_u32_e64 s[50:51], 0, v0
	v_and_b32_e32 v0, s64, v251
	v_cmp_ne_u32_e64 s[48:49], 0, v0
	v_and_b32_e32 v0, s64, v249
	v_cmp_ne_u32_e64 s[46:47], 0, v0
	v_and_b32_e32 v0, s64, v248
	v_cmp_ne_u32_e64 s[42:43], 0, v0
	s_mov_b64 s[86:87], s[50:51]
	s_mov_b64 s[88:89], s[48:49]
	s_mov_b64 s[90:91], s[46:47]
	s_mov_b64 s[92:93], s[42:43]
	s_or_b64 s[2:3], s[48:49], s[50:51]
	s_or_b64 s[2:3], s[2:3], s[46:47]
	s_or_b64 s[2:3], s[2:3], s[42:43]
	s_cmp_eq_u64 s[2:3], 0
	s_cbranch_scc1 .LBB0_754
	s_setprio 2
	ds_read_b128 v[182:185], v246 offset:16384
	ds_read_b128 v[178:181], v246 offset:18432
	ds_read_b128 v[186:189], v247 offset:16384
	ds_read_b128 v[174:177], v247 offset:18432
	ds_read_b128 v[158:161], v244 offset:20480
	ds_read_b128 v[162:165], v244 offset:21504
	ds_read_b128 v[166:169], v244 offset:22528
	ds_read_b128 v[170:173], v244 offset:23552
	s_add_i32 s2, s28, 0xffffff3f
	s_cmp_le_i32 s2, s26
	s_cselect_b64 s[2:3], -1, 0
	v_cndmask_b32_e64 v0, 0, 1, s[2:3]
	s_cmp_eq_u64 s[50:51], 0
	v_cmp_ne_u32_e64 s[44:45], 1, v0
	s_cbranch_scc1 .LBB0_822
	v_cndmask_b32_e64 v190, v194, 0, s[50:51]
	v_cndmask_b32_e64 v191, v194, 0, s[50:51]
	v_cndmask_b32_e64 v192, v194, 0, s[50:51]
	v_cndmask_b32_e64 v193, v194, 0, s[50:51]
	s_nop 0
	s_waitcnt lgkmcnt(7)
	v_mfma_f32_16x16x32_bf16 v[0:3], v[182:185], v[104:107], v[190:193]
	s_and_b64 vcc, exec, s[44:45]
	s_mov_b64 s[40:41], -1
	s_waitcnt lgkmcnt(6)
	v_mfma_f32_16x16x32_bf16 v[4:7], v[178:181], v[104:107], v[190:193]
	s_waitcnt lgkmcnt(5)
	v_mfma_f32_16x16x32_bf16 v[0:3], v[186:189], v[108:111], v[0:3]
	s_waitcnt lgkmcnt(4)
	v_mfma_f32_16x16x32_bf16 v[4:7], v[174:177], v[108:111], v[4:7]
	s_nop 5
	v_exp_f32_e32 v0, v0
	v_exp_f32_e32 v1, v1
	v_exp_f32_e32 v2, v2
	v_exp_f32_e32 v3, v3
	v_exp_f32_e32 v4, v4
	v_exp_f32_e32 v5, v5
	v_exp_f32_e32 v6, v6
	v_exp_f32_e32 v7, v7
	s_cbranch_vccz .LBB0_821

.Lsel_have_words2:
	v_and_b32_e32 v0, s70, v250
	v_cmp_ne_u32_e64 s[50:51], 0, v0
	v_and_b32_e32 v0, s70, v251
	v_cmp_ne_u32_e64 s[48:49], 0, v0
	v_and_b32_e32 v0, s70, v249
	v_cmp_ne_u32_e64 s[46:47], 0, v0
	v_and_b32_e32 v0, s70, v248
	v_cmp_ne_u32_e64 s[42:43], 0, v0
	s_mov_b64 s[86:87], s[50:51]
	s_mov_b64 s[88:89], s[48:49]
	s_mov_b64 s[90:91], s[46:47]
	s_mov_b64 s[92:93], s[42:43]
	s_or_b64 s[2:3], s[48:49], s[50:51]
	s_or_b64 s[2:3], s[2:3], s[46:47]
	s_or_b64 s[2:3], s[2:3], s[42:43]
	s_cmp_eq_u64 s[2:3], 0
	s_cbranch_scc1 .LB2_810
	s_setprio 2
	ds_read_b128 v[182:185], v246 offset:32768
	ds_read_b128 v[178:181], v246 offset:34816
	ds_read_b128 v[186:189], v247 offset:32768
	ds_read_b128 v[174:177], v247 offset:34816
	ds_read_b128 v[158:161], v244 offset:36864
	ds_read_b128 v[162:165], v244 offset:37888
	ds_read_b128 v[166:169], v244 offset:38912
	ds_read_b128 v[170:173], v244 offset:39936
	s_add_i32 s2, s28, 0xfffffeff
	s_cmp_le_i32 s2, s26
	s_cselect_b64 s[2:3], -1, 0
	v_cndmask_b32_e64 v0, 0, 1, s[2:3]
	s_cmp_eq_u64 s[50:51], 0
	v_cmp_ne_u32_e64 s[44:45], 1, v0
	s_cbranch_scc1 .LB2_767
	v_cndmask_b32_e64 v190, v194, 0, s[50:51]
	v_cndmask_b32_e64 v191, v194, 0, s[50:51]
	v_cndmask_b32_e64 v192, v194, 0, s[50:51]
	v_cndmask_b32_e64 v193, v194, 0, s[50:51]
	s_nop 0
	s_waitcnt lgkmcnt(7)
	v_mfma_f32_16x16x32_bf16 v[0:3], v[182:185], v[104:107], v[190:193]
	s_and_b64 vcc, exec, s[44:45]
	s_mov_b64 s[64:65], -1
	s_waitcnt lgkmcnt(6)
	v_mfma_f32_16x16x32_bf16 v[4:7], v[178:181], v[104:107], v[190:193]
	s_waitcnt lgkmcnt(5)
	v_mfma_f32_16x16x32_bf16 v[0:3], v[186:189], v[108:111], v[0:3]
	s_waitcnt lgkmcnt(4)
	v_mfma_f32_16x16x32_bf16 v[4:7], v[174:177], v[108:111], v[4:7]
	s_nop 5
	v_exp_f32_e32 v0, v0
	v_exp_f32_e32 v1, v1
	v_exp_f32_e32 v2, v2
	v_exp_f32_e32 v3, v3
	v_exp_f32_e32 v4, v4
	v_exp_f32_e32 v5, v5
	v_exp_f32_e32 v6, v6
	v_exp_f32_e32 v7, v7
	s_cbranch_vccz .LB2_766

.LB2_815:
	s_setprio 0
	s_add_i32 s2, s27, -3
	s_lshl_b32 s64, 1, s2
	v_and_b32_e32 v0, s64, v250
	v_cmp_ne_u32_e64 s[50:51], 0, v0
	v_and_b32_e32 v0, s64, v251
	v_cmp_ne_u32_e64 s[48:49], 0, v0
	v_and_b32_e32 v0, s64, v249
	v_cmp_ne_u32_e64 s[46:47], 0, v0
	v_and_b32_e32 v0, s64, v248
	v_cmp_ne_u32_e64 s[42:43], 0, v0
	s_mov_b64 s[86:87], s[50:51]
	s_mov_b64 s[88:89], s[48:49]
	s_mov_b64 s[90:91], s[46:47]
	s_mov_b64 s[92:93], s[42:43]
	s_or_b64 s[2:3], s[48:49], s[50:51]
	s_or_b64 s[2:3], s[2:3], s[46:47]
	s_or_b64 s[2:3], s[2:3], s[42:43]
	s_cmp_eq_u64 s[2:3], 0
	s_cbranch_scc1 .LB2_754
	s_setprio 2
	ds_read_b128 v[182:185], v246 offset:49152
	ds_read_b128 v[178:181], v246 offset:51200
	ds_read_b128 v[186:189], v247 offset:49152
	ds_read_b128 v[174:177], v247 offset:51200
	ds_read_b128 v[158:161], v244 offset:53248
	ds_read_b128 v[162:165], v244 offset:54272
	ds_read_b128 v[166:169], v244 offset:55296
	ds_read_b128 v[170:173], v244 offset:56320
	s_add_i32 s2, s28, 0xffffff3f
	s_cmp_le_i32 s2, s26
	s_cselect_b64 s[2:3], -1, 0
	v_cndmask_b32_e64 v0, 0, 1, s[2:3]
	s_cmp_eq_u64 s[50:51], 0
	v_cmp_ne_u32_e64 s[44:45], 1, v0
	s_cbranch_scc1 .LB2_822
	v_cndmask_b32_e64 v190, v194, 0, s[50:51]
	v_cndmask_b32_e64 v191, v194, 0, s[50:51]
	v_cndmask_b32_e64 v192, v194, 0, s[50:51]
	v_cndmask_b32_e64 v193, v194, 0, s[50:51]
	s_nop 0
	s_waitcnt lgkmcnt(7)
	v_mfma_f32_16x16x32_bf16 v[0:3], v[182:185], v[104:107], v[190:193]
	s_and_b64 vcc, exec, s[44:45]
	s_mov_b64 s[40:41], -1
	s_waitcnt lgkmcnt(6)
	v_mfma_f32_16x16x32_bf16 v[4:7], v[178:181], v[104:107], v[190:193]
	s_waitcnt lgkmcnt(5)
	v_mfma_f32_16x16x32_bf16 v[0:3], v[186:189], v[108:111], v[0:3]
	s_waitcnt lgkmcnt(4)
	v_mfma_f32_16x16x32_bf16 v[4:7], v[174:177], v[108:111], v[4:7]
	s_nop 5
	v_exp_f32_e32 v0, v0
	v_exp_f32_e32 v1, v1
	v_exp_f32_e32 v2, v2
	v_exp_f32_e32 v3, v3
	v_exp_f32_e32 v4, v4
	v_exp_f32_e32 v5, v5
	v_exp_f32_e32 v6, v6
	v_exp_f32_e32 v7, v7
	s_cbranch_vccz .LB2_821
